# attention per-tile K/V prefetch addresses: 64-bit VGPR math replaced by scalar base + per-lane 32-bit offset (saddr form, immediates for K/V and halves)
# baseline (speedup 1.0000x reference)
; #define LAS __attribute__((address_space(3)))
; __device__ __forceinline__ unsigned pk2(float lo, float hi) { f32x2_t v = {lo, hi}; bf16x2_t b = __builtin_convertvector(v, bf16x2_t); return __builtin_bit_cast(unsigned, b); }
; __device__ __forceinline__ void unpack8(u32x4v w, float* f) { f[0] = bflo(w.x); f[1] = bfhi(w.x); f[2] = bflo(w.y); f[3] = bfhi(w.y); f[4] = bflo(w.z); f[5] = bfhi(w.z); f[6] = bflo(w.w); f[7] = bfhi(w.w); }
; __device__ __forceinline__ void attn_unit(const Args& c, int l, int b, int h, int qb, float lam, float lam_init, LAS unsigned char* lds) {
;     ...
;     for (int kt = 0; kt < NT; ++kt) {
;         __syncthreads();
; #pragma unroll
;         for (int hh = 0; hh < 2; ++hh) {
;             const int kr = skey + 64 * hh;
;             float f[16]; unpack8(gk0[hh], f); unpack8(gk1[hh], f + 8);
;             float kw[16];
; #pragma unroll
;             for (int e4 = 0; e4 < 4; ++e4) { const f32x4 t4 = ((const f32x4*)kwp)[e4]; kw[4 * e4] = t4.x; kw[4 * e4 + 1] = t4.y; kw[4 * e4 + 2] = t4.z; kw[4 * e4 + 3] = t4.w; }
;             float ss = 0.f;
; #pragma unroll
;             for (int e = 0; e < 16; ++e) ss += f[e] * f[e];
;             ss += __shfl_xor(ss, 1); ss += __shfl_xor(ss, 2);
;             const float sc = rsqrtf(ss * (1.f / 64.f) + 1e-6f);
;             u32x4v o;
;             o.x = pk2(f[0] * sc * kw[0], f[1] * sc * kw[1]); o.y = pk2(f[2] * sc * kw[2], f[3] * sc * kw[3]); o.z = pk2(f[4] * sc * kw[4], f[5] * sc * kw[5]); o.w = pk2(f[6] * sc * kw[6], f[7] * sc * kw[7]);
;             *(LAS u32x4v*)(Kt + kr * 136 + part * 16) = o;
;             o.x = pk2(f[8] * sc * kw[8], f[9] * sc * kw[9]); o.y = pk2(f[10] * sc * kw[10], f[11] * sc * kw[11]); o.z = pk2(f[12] * sc * kw[12], f[13] * sc * kw[13]); o.w = pk2(f[14] * sc * kw[14], f[15] * sc * kw[15]);
;             *(LAS u32x4v*)(Kt + kr * 136 + part * 16 + 8) = o;
;             *(LAS u32x4v*)(Vs + kr * 136 + part * 16) = gv0[hh]; *(LAS u32x4v*)(Vs + kr * 136 + part * 16 + 8) = gv1[hh];
;         }
;         if (kt + 1 < NT) ATT_FETCH(kt + 1);
.LBB0_245:
	s_waitcnt lgkmcnt(0)
	s_barrier
	s_waitcnt vmcnt(0)
	ds_write_b128 v211, v[66:69]
	ds_write_b128 v211, v[70:73] offset:16
	ds_write_b128 v211, v[90:93] offset:17408
	ds_write_b128 v211, v[94:97] offset:17424
	ds_write_b128 v211, v[78:81] offset:34816
	ds_write_b128 v211, v[82:85] offset:34832
	ds_write_b128 v211, v[98:101] offset:52224
	ds_write_b128 v211, v[102:105] offset:52240
	s_cmp_ge_u32 s35, s22
	s_cbranch_scc1 .LBB0_247
	s_add_i32 s8, s18, s5
	s_addk_i32 s8, 0x80
	s_mul_i32 s8, s8, s27
	s_mov_b32 s21, s15
	s_mov_b32 s29, s15
	s_add_u32 s6, s2, s8
	s_addc_u32 s7, s3, 0
	s_add_u32 s6, s6, s20
	s_addc_u32 s7, s7, 0
	v_mul_u32_u24_e32 v188, s27, v186
	v_add_u32_e32 v188, v188, v0
	v_add_u32_e32 v189, 0xe0000, v188
	global_load_dwordx4 v[66:69], v188, s[6:7]
	global_load_dwordx4 v[70:73], v188, s[6:7] offset:16
	global_load_dwordx4 v[78:81], v188, s[6:7] offset:2048
	global_load_dwordx4 v[82:85], v188, s[6:7] offset:2064
	global_load_dwordx4 v[90:93], v189, s[6:7]
	global_load_dwordx4 v[94:97], v189, s[6:7] offset:16
	global_load_dwordx4 v[98:101], v189, s[6:7] offset:2048
	global_load_dwordx4 v[102:105], v189, s[6:7] offset:2064
